# grid barrier release: waiting workgroups poll the cross-XCD generation word directly, per-XCD re-publish atomic removed
# speedup vs baseline: 1.0061x; 1.0050x over previous
.LBB0_157:
	s_or_b64 exec, exec, s[10:11]
	v_cvt_f32_u32_e32 v4, v2
	s_waitcnt vmcnt(0)
	v_readfirstlane_b32 s0, v3
	v_sub_u32_e32 v3, 0, v2
	v_rcp_iflag_f32_e32 v4, v4
	v_add_u32_e32 v5, s0, v1
	v_mul_f32_e32 v4, 0x4f7ffffe, v4
	v_cvt_u32_f32_e32 v4, v4
	v_mul_lo_u32 v1, v3, v4
	v_mul_hi_u32 v1, v4, v1
	v_add_u32_e32 v1, v4, v1
	v_mul_hi_u32 v1, v5, v1
	v_mul_lo_u32 v3, v1, v2
	v_sub_u32_e32 v3, v5, v3
	v_add_u32_e32 v4, 1, v1
	v_cmp_ge_u32_e32 vcc, v3, v2
	s_nop 1
	v_cndmask_b32_e32 v1, v1, v4, vcc
	v_sub_u32_e32 v4, v3, v2
	v_cndmask_b32_e32 v3, v3, v4, vcc
	v_add_u32_e32 v4, 1, v1
	v_cmp_ge_u32_e32 vcc, v3, v2
	v_add_u32_e32 v3, 1, v5
	s_nop 0
	v_cndmask_b32_e32 v1, v1, v4, vcc
	v_mul_lo_u32 v4, v2, v1
	v_add_u32_e32 v2, v4, v2
	v_cmp_ne_u32_e32 vcc, v3, v2
	s_and_saveexec_b64 s[0:1], vcc
	s_xor_b64 s[10:11], exec, s[0:1]
	s_cbranch_execz .LBB0_171
	s_waitcnt lgkmcnt(0)
	s_add_u32 s16, s6, 0xe803500
	s_addc_u32 s17, s7, 0
	v_mov_b32_e32 v0, 0
	global_load_dword v0, v0, s[16:17] sc1
	s_waitcnt vmcnt(0)
	v_cmp_eq_u32_e32 vcc, v0, v1
	s_and_saveexec_b64 s[12:13], vcc
	s_cbranch_execz .LBB0_170
	s_add_u32 s14, s6, 0xe800200
	s_addc_u32 s15, s7, 0
	s_mov_b32 s2, 1
	s_mov_b64 s[18:19], 0
	v_mov_b32_e32 v0, 0
	s_branch .LBB0_161

.LBB0_188:
	s_or_b64 exec, exec, s[6:7]
	s_mov_b64 s[0:1], exec
	v_mbcnt_lo_u32_b32 v0, s0, 0
	v_mbcnt_hi_u32_b32 v0, s1, v0
	v_cmp_eq_u32_e32 vcc, 0, v0
	s_waitcnt vmcnt(0)
	buffer_inv sc1
	s_and_saveexec_b64 s[6:7], vcc
	s_cbranch_execz .LBB0_190
	s_bcnt1_i32_b64 s0, s[0:1]
	v_mov_b32_e32 v0, 0x2000
	v_mov_b32_e32 v1, s0
.LBB0_190:
	s_or_b64 exec, exec, s[6:7]
	s_waitcnt vmcnt(0)

.LBB0_354:
	s_or_b64 exec, exec, s[14:15]
	v_cvt_f32_u32_e32 v5, v3
	s_waitcnt vmcnt(0)
	v_readfirstlane_b32 s0, v4
	v_sub_u32_e32 v4, 0, v3
	v_rcp_iflag_f32_e32 v5, v5
	v_add_u32_e32 v6, s0, v0
	v_mul_f32_e32 v5, 0x4f7ffffe, v5
	v_cvt_u32_f32_e32 v5, v5
	v_mul_lo_u32 v0, v4, v5
	v_mul_hi_u32 v0, v5, v0
	v_add_u32_e32 v0, v5, v0
	v_mul_hi_u32 v0, v6, v0
	v_mul_lo_u32 v4, v0, v3
	v_sub_u32_e32 v4, v6, v4
	v_add_u32_e32 v5, 1, v0
	v_cmp_ge_u32_e32 vcc, v4, v3
	s_nop 1
	v_cndmask_b32_e32 v0, v0, v5, vcc
	v_sub_u32_e32 v5, v4, v3
	v_cndmask_b32_e32 v4, v4, v5, vcc
	v_add_u32_e32 v5, 1, v0
	v_cmp_ge_u32_e32 vcc, v4, v3
	v_add_u32_e32 v4, 1, v6
	s_nop 0
	v_cndmask_b32_e32 v0, v0, v5, vcc
	v_mul_lo_u32 v5, v3, v0
	v_add_u32_e32 v3, v5, v3
	v_cmp_ne_u32_e32 vcc, v4, v3
	s_and_saveexec_b64 s[0:1], vcc
	s_xor_b64 s[10:11], exec, s[0:1]
	s_cbranch_execz .LBB0_368
	s_waitcnt lgkmcnt(0)
	s_add_u32 s18, s6, 0xe803500
	s_addc_u32 s19, s7, 0
	v_mov_b32_e32 v2, 0
	global_load_dword v2, v2, s[18:19] sc1
	s_waitcnt vmcnt(0)
	v_cmp_eq_u32_e32 vcc, v2, v0
	s_and_saveexec_b64 s[14:15], vcc
	s_cbranch_execz .LBB0_367
	s_add_u32 s16, s6, 0xe800200
	s_addc_u32 s17, s7, 0
	s_mov_b32 s0, 1
	s_mov_b64 s[20:21], 0
	s_branch .LBB0_358

.LBB0_385:
	s_or_b64 exec, exec, s[6:7]
	s_mov_b64 s[6:7], exec
	v_mbcnt_lo_u32_b32 v0, s6, 0
	v_mbcnt_hi_u32_b32 v0, s7, v0
	v_cmp_eq_u32_e32 vcc, 0, v0
	s_waitcnt vmcnt(0)
	buffer_inv sc1
	s_and_saveexec_b64 s[10:11], vcc
	s_cbranch_execz .LBB0_387
	s_bcnt1_i32_b64 s0, s[6:7]
	v_mov_b32_e32 v0, s0
	v_mov_b32_e32 v2, 0x2000
.LBB0_387:
	s_or_b64 exec, exec, s[10:11]
	s_waitcnt vmcnt(0)

.LBB0_480:
	s_or_b64 exec, exec, s[12:13]
	v_cvt_f32_u32_e32 v5, v3
	s_waitcnt vmcnt(0)
	v_readfirstlane_b32 s0, v4
	v_sub_u32_e32 v4, 0, v3
	v_rcp_iflag_f32_e32 v5, v5
	v_add_u32_e32 v6, s0, v0
	v_mul_f32_e32 v5, 0x4f7ffffe, v5
	v_cvt_u32_f32_e32 v5, v5
	v_mul_lo_u32 v0, v4, v5
	v_mul_hi_u32 v0, v5, v0
	v_add_u32_e32 v0, v5, v0
	v_mul_hi_u32 v0, v6, v0
	v_mul_lo_u32 v4, v0, v3
	v_sub_u32_e32 v4, v6, v4
	v_add_u32_e32 v5, 1, v0
	v_cmp_ge_u32_e32 vcc, v4, v3
	s_nop 1
	v_cndmask_b32_e32 v0, v0, v5, vcc
	v_sub_u32_e32 v5, v4, v3
	v_cndmask_b32_e32 v4, v4, v5, vcc
	v_add_u32_e32 v5, 1, v0
	v_cmp_ge_u32_e32 vcc, v4, v3
	v_add_u32_e32 v4, 1, v6
	s_nop 0
	v_cndmask_b32_e32 v0, v0, v5, vcc
	v_mul_lo_u32 v5, v3, v0
	v_add_u32_e32 v3, v5, v3
	v_cmp_ne_u32_e32 vcc, v4, v3
	s_and_saveexec_b64 s[0:1], vcc
	s_xor_b64 s[10:11], exec, s[0:1]
	s_cbranch_execz .LBB0_494
	s_waitcnt lgkmcnt(0)
	s_add_u32 s16, s6, 0xe803500
	s_addc_u32 s17, s7, 0
	v_mov_b32_e32 v2, 0
	global_load_dword v2, v2, s[16:17] sc1
	s_waitcnt vmcnt(0)
	v_cmp_eq_u32_e32 vcc, v2, v0
	s_and_saveexec_b64 s[12:13], vcc
	s_cbranch_execz .LBB0_493
	s_add_u32 s14, s6, 0xe800200
	s_addc_u32 s15, s7, 0
	s_mov_b32 s0, 1
	s_mov_b64 s[18:19], 0
	s_branch .LBB0_484

.LBB0_511:
	s_or_b64 exec, exec, s[6:7]
	s_mov_b64 s[6:7], exec
	v_mbcnt_lo_u32_b32 v0, s6, 0
	v_mbcnt_hi_u32_b32 v0, s7, v0
	v_cmp_eq_u32_e32 vcc, 0, v0
	s_waitcnt vmcnt(0)
	buffer_inv sc1
	s_and_saveexec_b64 s[10:11], vcc
	s_cbranch_execz .LBB0_513
	s_bcnt1_i32_b64 s0, s[6:7]
	v_mov_b32_e32 v0, s0
	v_mov_b32_e32 v2, 0x2000
.LBB0_513:
	s_or_b64 exec, exec, s[10:11]
	s_waitcnt vmcnt(0)

.LBB0_590:
	s_or_b64 exec, exec, s[6:7]
	s_mov_b64 s[6:7], exec
	v_mbcnt_lo_u32_b32 v0, s6, 0
	v_mbcnt_hi_u32_b32 v0, s7, v0
	v_cmp_eq_u32_e32 vcc, 0, v0
	s_waitcnt vmcnt(0)
	buffer_inv sc1
	s_and_saveexec_b64 s[10:11], vcc
	s_cbranch_execz .LBB0_592
	s_bcnt1_i32_b64 s0, s[6:7]
	v_mov_b32_e32 v0, s0
	v_mov_b32_e32 v2, 0x2000
.LBB0_592:
	s_or_b64 exec, exec, s[10:11]
	s_waitcnt vmcnt(0)

.LBB0_687:
	s_or_b64 exec, exec, s[6:7]
	s_mov_b64 s[6:7], exec
	v_mbcnt_lo_u32_b32 v0, s6, 0
	v_mbcnt_hi_u32_b32 v0, s7, v0
	v_cmp_eq_u32_e32 vcc, 0, v0
	s_waitcnt vmcnt(0)
	buffer_inv sc1
	s_and_saveexec_b64 s[10:11], vcc
	s_cbranch_execz .LBB0_689
	s_bcnt1_i32_b64 s0, s[6:7]
	v_mov_b32_e32 v0, s0
	v_mov_b32_e32 v2, 0x2000
.LBB0_689:
	s_or_b64 exec, exec, s[10:11]
	s_waitcnt vmcnt(0)

.LBB0_952:
	s_or_b64 exec, exec, s[6:7]
	s_mov_b64 s[6:7], exec
	v_mbcnt_lo_u32_b32 v0, s6, 0
	v_mbcnt_hi_u32_b32 v0, s7, v0
	v_cmp_eq_u32_e32 vcc, 0, v0
	s_waitcnt vmcnt(0)
	buffer_inv sc1
	s_and_saveexec_b64 s[10:11], vcc
	s_cbranch_execz .LBB0_954
	s_bcnt1_i32_b64 s0, s[6:7]
	v_mov_b32_e32 v0, s0
	v_mov_b32_e32 v2, 0x2000
.LBB0_954:
	s_or_b64 exec, exec, s[10:11]
	s_waitcnt vmcnt(0)

.LBB0_1219:
	s_or_b64 exec, exec, s[14:15]
	v_cvt_f32_u32_e32 v5, v3
	s_waitcnt vmcnt(0)
	v_readfirstlane_b32 s0, v4
	v_sub_u32_e32 v4, 0, v3
	v_rcp_iflag_f32_e32 v5, v5
	v_add_u32_e32 v6, s0, v0
	v_mul_f32_e32 v5, 0x4f7ffffe, v5
	v_cvt_u32_f32_e32 v5, v5
	v_mul_lo_u32 v0, v4, v5
	v_mul_hi_u32 v0, v5, v0
	v_add_u32_e32 v0, v5, v0
	v_mul_hi_u32 v0, v6, v0
	v_mul_lo_u32 v4, v0, v3
	v_sub_u32_e32 v4, v6, v4
	v_add_u32_e32 v5, 1, v0
	v_cmp_ge_u32_e32 vcc, v4, v3
	s_nop 1
	v_cndmask_b32_e32 v0, v0, v5, vcc
	v_sub_u32_e32 v5, v4, v3
	v_cndmask_b32_e32 v4, v4, v5, vcc
	v_add_u32_e32 v5, 1, v0
	v_cmp_ge_u32_e32 vcc, v4, v3
	v_add_u32_e32 v4, 1, v6
	s_nop 0
	v_cndmask_b32_e32 v0, v0, v5, vcc
	v_mul_lo_u32 v5, v3, v0
	v_add_u32_e32 v3, v5, v3
	v_cmp_ne_u32_e32 vcc, v4, v3
	s_and_saveexec_b64 s[0:1], vcc
	s_xor_b64 s[12:13], exec, s[0:1]
	s_cbranch_execz .LBB0_1233
	s_waitcnt lgkmcnt(0)
	s_add_u32 s18, s8, 0xe803500
	s_addc_u32 s19, s9, 0
	v_mov_b32_e32 v2, 0
	global_load_dword v2, v2, s[18:19] sc1
	s_waitcnt vmcnt(0)
	v_cmp_eq_u32_e32 vcc, v2, v0
	s_and_saveexec_b64 s[14:15], vcc
	s_cbranch_execz .LBB0_1232
	s_add_u32 s16, s8, 0xe800200
	s_addc_u32 s17, s9, 0
	s_mov_b32 s0, 1
	s_mov_b64 s[20:21], 0
	s_branch .LBB0_1223

.LBB0_1250:
	s_or_b64 exec, exec, s[8:9]
	s_mov_b64 s[8:9], exec
	v_mbcnt_lo_u32_b32 v0, s8, 0
	v_mbcnt_hi_u32_b32 v0, s9, v0
	v_cmp_eq_u32_e32 vcc, 0, v0
	s_waitcnt vmcnt(0)
	buffer_inv sc1
	s_and_saveexec_b64 s[12:13], vcc
	s_cbranch_execz .LBB0_1252
	s_bcnt1_i32_b64 s0, s[8:9]
	v_mov_b32_e32 v0, s0
	v_mov_b32_e32 v2, 0x2000
.LBB0_1252:
	s_or_b64 exec, exec, s[12:13]
	s_waitcnt vmcnt(0)

.LBB0_1307:
	s_or_b64 exec, exec, s[8:9]
	s_mov_b64 s[8:9], exec
	v_mbcnt_lo_u32_b32 v0, s8, 0
	v_mbcnt_hi_u32_b32 v0, s9, v0
	v_cmp_eq_u32_e32 vcc, 0, v0
	s_waitcnt vmcnt(0)
	buffer_inv sc1
	s_and_saveexec_b64 s[12:13], vcc
	s_cbranch_execz .LBB0_1309
	s_bcnt1_i32_b64 s0, s[8:9]
	v_mov_b32_e32 v0, s0
	v_mov_b32_e32 v2, 0x2000
.LBB0_1309:
	s_or_b64 exec, exec, s[12:13]
	s_waitcnt vmcnt(0)

.LBB0_1387:
	s_bcnt1_i32_b64 s0, s[6:7]
	v_mov_b32_e32 v0, s0
	v_mov_b32_e32 v2, 0x2000
	s_getpc_b64 s[98:99]
